# O5 + static s_setprio 1 for waves 4-7 inside the GQA and NAT attention phases (reset at each grid barrier)
# speedup vs baseline: 1.0121x; 1.0121x over previous
; __device__ __forceinline__ unsigned xb_add(unsigned* p, unsigned v) { return __hip_atomic_fetch_add(p, v, __ATOMIC_RELAXED, __HIP_MEMORY_SCOPE_AGENT); }
; __device__ __forceinline__ void xcd_barrier(const XcdBarrier& b, int tid) {
;     asm volatile("s_waitcnt vmcnt(0)" ::: "memory");
;     __syncthreads();
;     if (tid == 0) {
;         unsigned* bar = b.bar;
;         __builtin_amdgcn_s_waitcnt(0);
;         unsigned nloc = b.st[0], nx = b.st[1];
;         if (nloc == 0u) { xcd_barrier_complete(bar, b.x, nloc, nx); b.st[0] = nloc; b.st[1] = nx; }
;         const unsigned old = xb_add(&bar[XB_XSUB(b.x)], 1u);
.LBB0_44:
	s_xor_b64 s[0:1], s[46:47], -1
	s_cmp_lt_i32 s88, 2
	s_cselect_b64 s[2:3], -1, 0
	s_cmp_gt_i32 s89, 1
	s_cselect_b64 s[4:5], -1, 0
	s_and_b64 s[2:3], s[2:3], s[4:5]
	s_andn2_b64 vcc, exec, s[2:3]
	s_cbranch_vccnz .LBB0_155
	s_andn2_b64 vcc, exec, s[0:1]
	s_cbranch_vccnz .LBB0_95
	v_mbcnt_lo_u32_b32 v0, -1, 0
	v_mbcnt_hi_u32_b32 v0, -1, v0
	s_lshl_b32 s0, s84, 6
	s_waitcnt vmcnt(0)
	s_sub_i32 s0, 0, s0
	v_cmp_eq_u32_e32 vcc, s0, v0
	s_setprio 0
	s_barrier
	s_and_saveexec_b64 s[0:1], vcc
	s_cbranch_execz .LBB0_94
	v_mov_b32_e32 v0, s96
	s_waitcnt vmcnt(0) expcnt(0) lgkmcnt(0)
	ds_read_b32 v2, v0
	ds_read_b32 v0, v0 offset:4
	s_waitcnt lgkmcnt(1)
	v_cmp_ne_u32_e32 vcc, 0, v2
	s_cbranch_vccnz .LBB0_62
	v_readlane_b32 s2, v253, 0
	v_readlane_b32 s3, v253, 1
	s_load_dwordx2 s[6:7], s[2:3], 0x4
	s_add_u32 s2, s82, 0x4200
	s_addc_u32 s3, s83, 0
	s_add_u32 s4, s82, 0x4400
	s_addc_u32 s5, s83, 0
	v_readlane_b32 s8, v253, 2
	s_waitcnt lgkmcnt(0)
	s_mul_i32 s27, s6, s8
	s_add_u32 s6, s82, 0x4500
	s_mul_i32 s27, s27, s7
	s_addc_u32 s7, s83, 0
	s_add_u32 s8, s82, 0x4600
	s_addc_u32 s9, s83, 0
	s_add_u32 s10, s82, 0x4700
	s_addc_u32 s11, s83, 0
	s_add_u32 s12, s82, 0x4800
	s_addc_u32 s13, s83, 0
	s_add_u32 s14, s82, 0x4900
	s_addc_u32 s15, s83, 0
	s_add_u32 s18, s82, 0x4a00
	s_addc_u32 s19, s83, 0
	s_add_u32 s20, s82, 0x4b00
	s_addc_u32 s21, s83, 0
	s_add_u32 s22, s82, 0x4c00
	s_addc_u32 s23, s83, 0
	s_add_u32 s24, s82, 0x4d00
	s_addc_u32 s25, s83, 0
	s_add_u32 s28, s82, 0x4e00
	s_addc_u32 s29, s83, 0
	s_add_u32 s30, s82, 0x4f00
	s_addc_u32 s31, s83, 0
	s_add_u32 s34, s82, 0x5000
	s_addc_u32 s35, s83, 0
	s_add_u32 s36, s82, 0x5100
	s_addc_u32 s37, s83, 0
	s_add_u32 s38, s82, 0x5200
	s_addc_u32 s39, s83, 0
	s_add_u32 s40, s82, 0x5300
	s_addc_u32 s41, s83, 0
	s_mov_b32 s33, 1
	v_mov_b32_e32 v16, 0
	s_branch .LBB0_50

; __device__ __forceinline__ unsigned xb_add(unsigned* p, unsigned v) { return __hip_atomic_fetch_add(p, v, __ATOMIC_RELAXED, __HIP_MEMORY_SCOPE_AGENT); }
; #define PH_BEGIN(gp) if (lo <= (gp) && (gp) < hi) { if (!first) xcd_barrier(bar, tid_here(F.wave)); first = false; F.bid = blockIdx.x; asm volatile("" : "+s"(F.ws), "+s"(F.G), "+s"(F.vcu), "+s"(F.bid), "+s"(F.wave)); F.tid = tid_here(F.wave); F.lane = F.tid & 63;
; __device__ __forceinline__ void xcd_barrier(const XcdBarrier& b, int tid) {
;     asm volatile("s_waitcnt vmcnt(0)" ::: "memory");
;     __syncthreads();
;     if (tid == 0) {
;         unsigned* bar = b.bar;
;         __builtin_amdgcn_s_waitcnt(0);
;         unsigned nloc = b.st[0], nx = b.st[1];
;         if (nloc == 0u) { xcd_barrier_complete(bar, b.x, nloc, nx); b.st[0] = nloc; b.st[1] = nx; }
;         const unsigned old = xb_add(&bar[XB_XSUB(b.x)], 1u);
; __global__ void __launch_bounds__(512, 2) fwd_kernel(Args args) {
;     ...
;     for (int layer = 0; layer < DEPTH; ++layer) {
;         const int kind = layer % 3, j = layer / 3, gp0 = 2 + 8 * layer;
;         const bool need_ctx = layer < DEPTH - 1;
;         const gf32* ada_l = WSF(WS_ADA) + (size_t)layer * 3 * 6 * DM;
;         gf32* st1 = WSF(WS_STATS) + (size_t)(2 * layer) * MROWS;
;         gf32* st2 = st1 + MROWS;
;         if (kind == 0) {
;             PH_BEGIN(gp0 + 1) if (EN & 4) phase_pool(F, st1, !need_ctx, layer); PH_END
.LBB0_156:
	v_readlane_b32 s0, v253, 8
	v_readlane_b32 s1, v253, 9
	s_xor_b64 s[0:1], s[0:1], -1
	v_writelane_b32 v254, s0, 39
	v_readlane_b32 s6, v253, 6
	v_readlane_b32 s7, v253, 7
	v_writelane_b32 v254, s1, 40
	s_mov_b64 s[24:25], 0
	v_readlane_b32 s2, v254, 23
	s_cmp_lg_u32 s2, 3
	s_cselect_b64 s[0:1], -1, 0
	v_writelane_b32 v254, s0, 41
	s_cmp_eq_u32 s2, 3
	s_mul_i32 s48, s2, 0x4400
	v_writelane_b32 v254, s1, 42
	s_cselect_b64 s[0:1], -1, 0
	v_writelane_b32 v254, s0, 43
	s_nop 1
	v_writelane_b32 v254, s1, 44
	s_and_b64 s[0:1], s[0:1], exec
	s_cselect_b32 s5, 0, s2
	s_lshl_b32 s4, s2, 3
	s_mul_i32 s1, s2, 0x24000
	s_mul_hi_u32 s0, s2, 0x24000
	v_writelane_b32 v254, s1, 45
	s_add_u32 s1, s6, s1
	s_addc_u32 s0, s7, s0
	s_add_u32 s1, s1, 0x200000
	v_writelane_b32 v254, s1, 46
	s_addc_u32 s0, s0, 0
	v_writelane_b32 v254, s0, 47
	s_lshl_b64 s[0:1], s[48:49], 2
	s_add_u32 s0, s6, s0
	s_addc_u32 s1, s7, s1
	s_add_u32 s2, s0, 0x10000
	s_addc_u32 s3, s1, 0
	v_writelane_b32 v254, s2, 48
	s_add_u32 s0, s0, 0x18800
	s_nop 0
	v_writelane_b32 v254, s3, 49
	v_writelane_b32 v254, s0, 50
	s_addc_u32 s0, s1, 0
	s_or_b32 s2, s4, 3
	s_cmp_le_i32 s88, s2
	v_writelane_b32 v254, s0, 52
	s_cselect_b64 s[0:1], -1, 0
	s_cmp_lt_i32 s2, s89
	s_cselect_b64 s[2:3], -1, 0
	s_and_b64 s[80:81], s[0:1], s[2:3]
	v_writelane_b32 v254, s4, 54
	s_mov_b64 s[2:3], -1
	v_writelane_b32 v254, s5, 55
	s_cmp_lt_i32 s5, 1
	s_mov_b64 s[0:1], 0
	s_cbranch_scc1 .LBB0_464
	v_readlane_b32 s0, v254, 55
	s_cmp_eq_u32 s0, 1
	s_mov_b64 s[0:1], -1
	s_cbranch_scc0 .LBB0_463
	v_readlane_b32 s0, v253, 4
	s_mov_b32 s82, s0
	v_readlane_b32 s0, v253, 3
	v_readlane_b32 s42, v253, 8
	v_readlane_b32 s46, v253, 6
	v_writelane_b32 v254, s0, 58
	v_readlane_b32 s0, v253, 10
	s_andn2_b64 vcc, exec, s[80:81]
	v_readlane_b32 s43, v253, 9
	v_writelane_b32 v254, s0, 59
	v_readlane_b32 s47, v253, 7
	v_readlane_b32 s1, v253, 5
	s_cbranch_vccnz .LBB0_360
	v_readlane_b32 s0, v254, 39
	v_readlane_b32 s1, v254, 40
	s_andn2_b64 vcc, exec, s[0:1]
	s_cbranch_vccnz .LBB0_209
	v_readlane_b32 s0, v253, 10
	v_mbcnt_lo_u32_b32 v0, -1, 0
	v_mbcnt_hi_u32_b32 v0, -1, v0
	s_lshl_b32 s0, s0, 6
	s_waitcnt vmcnt(0)
	s_sub_i32 s0, 0, s0
	v_cmp_eq_u32_e32 vcc, s0, v0
	s_setprio 0
	s_barrier
	s_and_saveexec_b64 s[0:1], vcc
	s_cbranch_execz .LBB0_208
	v_mov_b32_e32 v0, s96
	s_waitcnt vmcnt(0) expcnt(0) lgkmcnt(0)
	ds_read_b32 v2, v0
	ds_read_b32 v0, v0 offset:4
	s_waitcnt lgkmcnt(1)
	v_cmp_ne_u32_e32 vcc, 0, v2
	s_cbranch_vccnz .LBB0_176
	v_readlane_b32 s4, v253, 0
	v_readlane_b32 s5, v253, 1
	s_load_dwordx2 s[2:3], s[4:5], 0x4
	v_readlane_b32 s4, v253, 2
	s_mov_b32 s9, 1
	s_waitcnt lgkmcnt(0)
	s_mul_i32 s8, s2, s4
	s_mul_i32 s8, s8, s3
	s_branch .LBB0_164

; __device__ __forceinline__ unsigned xb_add(unsigned* p, unsigned v) { return __hip_atomic_fetch_add(p, v, __ATOMIC_RELAXED, __HIP_MEMORY_SCOPE_AGENT); }
; #define PH_BEGIN(gp) if (lo <= (gp) && (gp) < hi) { if (!first) xcd_barrier(bar, tid_here(F.wave)); first = false; F.bid = blockIdx.x; asm volatile("" : "+s"(F.ws), "+s"(F.G), "+s"(F.vcu), "+s"(F.bid), "+s"(F.wave)); F.tid = tid_here(F.wave); F.lane = F.tid & 63;
; __device__ __forceinline__ void xcd_barrier(const XcdBarrier& b, int tid) {
;     asm volatile("s_waitcnt vmcnt(0)" ::: "memory");
;     __syncthreads();
;     if (tid == 0) {
;         unsigned* bar = b.bar;
;         __builtin_amdgcn_s_waitcnt(0);
;         unsigned nloc = b.st[0], nx = b.st[1];
;         if (nloc == 0u) { xcd_barrier_complete(bar, b.x, nloc, nx); b.st[0] = nloc; b.st[1] = nx; }
;         const unsigned old = xb_add(&bar[XB_XSUB(b.x)], 1u);
; __global__ void __launch_bounds__(512, 2) fwd_kernel(Args args) {
;     ...
;             PH_BEGIN(gp0 + 3) if (EN & 64) phase_attn_gqa(F, (char*)lds); PH_END
.LBB0_360:
	v_readlane_b32 s0, v254, 54
	s_or_b32 s2, s0, 5
	s_cmp_le_i32 s88, s2
	s_cselect_b64 s[0:1], -1, 0
	s_cmp_lt_i32 s2, s89
	s_cselect_b64 s[2:3], -1, 0
	s_and_b64 s[0:1], s[0:1], s[2:3]
	s_andn2_b64 vcc, exec, s[0:1]
	s_cbranch_vccnz .LBB0_462
	s_xor_b64 s[0:1], s[42:43], -1
	s_andn2_b64 vcc, exec, s[0:1]
	s_cbranch_vccnz .LBB0_411
	v_readlane_b32 s0, v254, 59
	v_mbcnt_lo_u32_b32 v0, -1, 0
	v_mbcnt_hi_u32_b32 v0, -1, v0
	s_lshl_b32 s0, s0, 6
	s_waitcnt vmcnt(0)
	s_sub_i32 s0, 0, s0
	v_cmp_eq_u32_e32 vcc, s0, v0
	s_waitcnt vmcnt(0) lgkmcnt(0)
	s_setprio 0
	s_barrier
	s_and_saveexec_b64 s[0:1], vcc
	s_cbranch_execz .LBB0_410
	v_mov_b32_e32 v0, s96
	s_waitcnt vmcnt(0) expcnt(0) lgkmcnt(0)
	ds_read_b32 v2, v0
	ds_read_b32 v0, v0 offset:4
	s_waitcnt lgkmcnt(1)
	v_cmp_ne_u32_e32 vcc, 0, v2
	s_cbranch_vccnz .LBB0_378
	v_readlane_b32 s4, v253, 0
	v_readlane_b32 s5, v253, 1
	s_load_dwordx2 s[2:3], s[4:5], 0x4
	v_readlane_b32 s4, v253, 2
	s_mov_b32 s9, 1
	s_waitcnt lgkmcnt(0)
	s_mul_i32 s8, s2, s4
	s_mul_i32 s8, s8, s3
	s_branch .LBB0_366

; __device__ __forceinline__ void phase_attn_gqa(Frame& F, char* lds) {
;     const gb16* Q = WSB(WS_Q); const gb16* Kp = WSB(WS_K); const gb16* Vp = WSB(WS_V); gb16* PO = WSB(WS_PO); const gf32* gqn = inp(F, I_GQN); const gf32* rope = WSF(WS_ROPE);
;     for (int u = F.vcu; u < 512 + 32; u += F.G) {
;         __syncthreads();
;         if (u < 512) { const int b = u >> 8, rem = u & 255, kvh = rem >> 6, gq = (rem >> 4) & 3, qb = rem & 15, h = kvh * 4 + gq;
;             const size_t qrow = (size_t)b * RB + CTXL + (size_t)qb * 256;
;             att::attn_unit<false, 2>(Q + qrow * DM + h * HD, Kp + (size_t)b * RB * 512 + kvh * HD, Vp + (size_t)b * RB * 512 + kvh * HD, PO + qrow * DM + h * HD, DM, 512, DM, RB / 64, 0, RB / 64, lds, 0, 0, gqn, rope, qb * 256, F.wave); }
.LBB0_411:
	s_mov_b32 s0, s97
	v_readlane_b32 s1, v254, 58
	v_readlane_b32 s2, v254, 59
	v_mbcnt_lo_u32_b32 v0, -1, 0
	v_mbcnt_hi_u32_b32 v0, -1, v0
	s_cmpk_gt_i32 s1, 0x21f
	s_nop 0
	v_writelane_b32 v254, s2, 59
	s_nop 0
	v_readlane_b32 s0, v254, 17
	v_writelane_b32 v254, s1, 58
	s_nop 0
	v_mov_b32_e32 v0, s0
	s_waitcnt lgkmcnt(0)
	ds_read_b64 v[0:1], v0
	s_waitcnt lgkmcnt(0)
	v_readfirstlane_b32 s37, v1
	v_readfirstlane_b32 s36, v0
	s_cbranch_scc1 .LBB0_461
	v_readlane_b32 s4, v254, 59
	s_cmp_lt_i32 s4, 4
	s_cbranch_scc1 .Lattg_lo
	s_setprio 1
.Lattg_lo:
	s_lshl_b32 s8, s4, 6
	s_add_u32 s9, s46, 0x8c00000
	s_addc_u32 s10, s47, 0
	s_add_u32 s11, s46, 0xae00000
	s_addc_u32 s12, s47, 0
	s_add_u32 s13, s46, 0xd000000
	s_addc_u32 s14, s47, 0
	s_add_u32 s15, s46, 0x6a00000
	s_addc_u32 s28, s47, 0
	s_add_u32 s38, s46, 0x300000
	s_addc_u32 s39, s47, 0
	s_lshl_b32 s0, s4, 8
	s_add_i32 s29, s0, 0
	s_lshl_b32 s30, s4, 2
	s_lshl_b32 s0, s4, 1
	s_and_b32 s1, s30, 0x3ffff0
	s_and_b32 s2, s0, 4
	s_and_b32 s44, s0, 2
	s_add_i32 s0, s4, 8
	s_or_b32 s31, s1, s2
	s_lshl_b32 s45, s0, 2
	s_lshl_b32 s1, s0, 1
	s_lshl_b32 s40, s4, 5
	s_and_b32 s2, s45, 0x3ffff0
	s_and_b32 s3, s1, 4
	s_ashr_i32 s41, s40, 31
	s_add_i32 s29, s29, 0x10000
	s_or_b32 s64, s2, s3
	s_and_b32 s65, s1, 2
	s_lshl_b32 s66, s4, 10
	s_lshl_b64 s[42:43], s[40:41], 12
	s_lshl_b32 s1, s4, 13
	s_cmp_lt_i32 s4, 4
	s_mov_b32 s2, 0x9800
	s_cselect_b32 s2, 0x8000, s2
	s_add_i32 s41, s1, 0
	s_lshl_b32 s67, s4, 12
	s_and_b32 s1, s4, 1
	s_and_b32 s0, s0, 1
	s_add_i32 s41, s41, s2
	s_add_i32 s68, s67, 0x8000
	s_lshl_b32 s69, s1, 7
	s_lshl_b32 s72, s0, 7
	v_readlane_b32 s73, v254, 58
	s_branch .LBB0_415

; __device__ __forceinline__ unsigned xb_add(unsigned* p, unsigned v) { return __hip_atomic_fetch_add(p, v, __ATOMIC_RELAXED, __HIP_MEMORY_SCOPE_AGENT); }
; __device__ __forceinline__ void xcd_barrier(const XcdBarrier& b, int tid) {
;     asm volatile("s_waitcnt vmcnt(0)" ::: "memory");
;     __syncthreads();
;     if (tid == 0) {
;         unsigned* bar = b.bar;
;         __builtin_amdgcn_s_waitcnt(0);
;         unsigned nloc = b.st[0], nx = b.st[1];
;         if (nloc == 0u) { xcd_barrier_complete(bar, b.x, nloc, nx); b.st[0] = nloc; b.st[1] = nx; }
;         const unsigned old = xb_add(&bar[XB_XSUB(b.x)], 1u);
.LBB0_466:
	v_cndmask_b32_e64 v0, 0, 1, s[80:81]
	s_andn2_b64 vcc, exec, s[0:1]
	v_cmp_ne_u32_e64 s[0:1], 1, v0
	s_nop 1
	v_writelane_b32 v254, s0, 56
	s_nop 1
	v_writelane_b32 v254, s1, 57
	s_cbranch_vccnz .LBB0_808
	v_readlane_b32 s0, v254, 56
	v_readlane_b32 s1, v254, 57
	s_and_b64 vcc, exec, s[0:1]
	v_readlane_b32 s0, v253, 4
	s_mov_b32 s82, s0
	v_readlane_b32 s0, v253, 3
	v_readlane_b32 s42, v253, 8
	v_readlane_b32 s46, v253, 6
	v_writelane_b32 v254, s0, 58
	v_readlane_b32 s0, v253, 10
	v_readlane_b32 s43, v253, 9
	v_readlane_b32 s47, v253, 7
	v_writelane_b32 v254, s0, 59
	v_readlane_b32 s1, v253, 5
	s_cbranch_vccnz .LBB0_569
	v_readlane_b32 s0, v254, 39
	v_readlane_b32 s1, v254, 40
	s_andn2_b64 vcc, exec, s[0:1]
	s_cbranch_vccnz .LBB0_518
	v_readlane_b32 s0, v253, 10
	v_mbcnt_lo_u32_b32 v0, -1, 0
	v_mbcnt_hi_u32_b32 v0, -1, v0
	s_lshl_b32 s0, s0, 6
	s_waitcnt vmcnt(0)
	s_sub_i32 s0, 0, s0
	v_cmp_eq_u32_e32 vcc, s0, v0
	s_waitcnt vmcnt(0) lgkmcnt(0)
	s_setprio 0
	s_barrier
	s_and_saveexec_b64 s[0:1], vcc
	s_cbranch_execz .LBB0_517
	v_mov_b32_e32 v0, s96
	s_waitcnt vmcnt(0) expcnt(0) lgkmcnt(0)
	ds_read_b32 v2, v0
	ds_read_b32 v0, v0 offset:4
	s_waitcnt lgkmcnt(1)
	v_cmp_ne_u32_e32 vcc, 0, v2
	s_cbranch_vccnz .LBB0_485
	v_readlane_b32 s4, v253, 0
	v_readlane_b32 s5, v253, 1
	s_load_dwordx2 s[2:3], s[4:5], 0x4
	v_readlane_b32 s4, v253, 2
	s_mov_b32 s9, 1
	s_waitcnt lgkmcnt(0)
	s_mul_i32 s8, s2, s4
	s_mul_i32 s8, s8, s3
	s_branch .LBB0_473

; __device__ __forceinline__ void phase_attn_nat(Frame& F, char* lds) {
;     const gb16* Q = WSB(WS_Q); const gb16* Kp = WSB(WS_K); const gb16* Vp = WSB(WS_V); gb16* PO = WSB(WS_PO); const gf32* rpb = inp(F, I_RPB);
;     for (int u = F.vcu; u < 512; u += F.G) {
;         __syncthreads();
;         { const int b = u >> 8, h = (u >> 4) & 15, qb = u & 15, r0 = 4 * qb;
;             const int kr_lo = min(max(r0 - 4, 0), 56), kr_hi = min(max(r0 + 3 - 4, 0), 56) + 8; int n2 = kr_hi - kr_lo; n2 += (n2 & 1);
;             { int bt = F.tid; asm volatile("" : "+v"(bt));
;               if (bt < att::NBIAS) ((float*)(lds + att::SHM_BIAS))[att::BIAS_PAD + bt] = rpb[h * att::NBIAS + bt] * 1.4426950408889634f; }
;             const size_t qrow = (size_t)b * RB + CTXL + (size_t)qb * 256;
;             att::attn_unit<true, 0>(Q + qrow * DM + h * HD, Kp + (size_t)b * RB * DM + h * HD, Vp + (size_t)b * RB * DM + h * HD, PO + qrow * DM + h * HD, DM, DM, DM, CTXL / 64, CTXL + kr_lo * 64, CTXL / 64 + n2, lds, r0, kr_lo, nullptr, nullptr, 0, F.wave); }
.LBB0_620:
	s_mov_b32 s0, s97
	v_readlane_b32 s2, v254, 58
	v_readlane_b32 s1, v254, 59
	s_lshl_b32 s28, s1, 6
	s_add_u32 s29, s46, 0x8c00000
	v_writelane_b32 v254, s1, 59
	s_addc_u32 s44, s47, 0
	v_readlane_b32 s0, v254, 18
	s_add_u32 s45, s46, 0xae00000
	v_mbcnt_lo_u32_b32 v0, -1, 0
	v_mbcnt_hi_u32_b32 v0, -1, v0
	s_addc_u32 s48, s47, 0
	s_waitcnt lgkmcnt(0)
	v_mov_b32_e32 v1, s0
	ds_read_b64 v[2:3], v1
	s_add_u32 s52, s46, 0xd000000
	s_addc_u32 s53, s47, 0
	s_add_u32 s54, s46, 0x6a00000
	s_addc_u32 s55, s47, 0
	s_waitcnt lgkmcnt(0)
	v_readfirstlane_b32 s1, v3
	v_writelane_b32 v254, s2, 58
	s_cmpk_gt_i32 s2, 0x1ff
	v_readfirstlane_b32 s0, v2
	s_cbranch_scc1 .LBB0_778
	s_lshl_b32 s2, s28, 2
	v_readlane_b32 s5, v254, 59
	s_cmp_lt_i32 s5, 4
	s_cbranch_scc1 .Lattn_lo
	s_setprio 1
.Lattn_lo:
	s_add_i32 s18, s2, 0
	s_lshl_b32 s2, s5, 1
	s_lshl_b32 s19, s5, 2
	s_and_b32 s4, s2, 4
	s_and_b32 s56, s2, 2
	s_add_i32 s2, s5, 8
	s_and_b32 s3, s19, 0xffff0
	s_lshl_b32 s57, s2, 2
	s_lshl_b32 s2, s2, 1
	s_lshl_b32 s30, s5, 5
	s_or_b32 s27, s3, s4
	s_and_b32 s3, s57, 0xffff0
	s_and_b32 s4, s2, 4
	s_ashr_i32 s31, s30, 31
	s_add_i32 s18, s18, 0x10000
	s_or_b32 s58, s3, s4
	s_and_b32 s59, s2, 2
	s_lshl_b32 s2, s5, 10
	s_ashr_i32 s60, s5, 1
	s_and_b32 s61, s30, 32
	s_lshl_b64 s[50:51], s[30:31], 12
	s_lshl_b32 s3, s5, 13
	s_cmp_lt_i32 s5, 4
	s_mov_b32 s4, 0x9800
	s_cselect_b32 s4, 0x8000, s4
	s_add_i32 s31, s3, 0
	v_readlane_b32 s65, v254, 58
	v_add_u32_e32 v202, s28, v0
	s_add_i32 s31, s31, s4
	s_sub_i32 s62, 0, s60
	s_add_i32 s63, s2, 0
	s_mov_b32 s64, s65
	s_branch .LBB0_623

; __device__ __forceinline__ unsigned xb_add(unsigned* p, unsigned v) { return __hip_atomic_fetch_add(p, v, __ATOMIC_RELAXED, __HIP_MEMORY_SCOPE_AGENT); }
; __device__ __forceinline__ void xcd_barrier(const XcdBarrier& b, int tid) {
;     asm volatile("s_waitcnt vmcnt(0)" ::: "memory");
;     __syncthreads();
;     if (tid == 0) {
;         unsigned* bar = b.bar;
;         __builtin_amdgcn_s_waitcnt(0);
;         unsigned nloc = b.st[0], nx = b.st[1];
;         if (nloc == 0u) { xcd_barrier_complete(bar, b.x, nloc, nx); b.st[0] = nloc; b.st[1] = nx; }
;         const unsigned old = xb_add(&bar[XB_XSUB(b.x)], 1u);
.LBB0_808:
	v_readlane_b32 s0, v254, 23
	s_lshl_b32 s48, s0, 12
	s_and_b64 vcc, exec, s[24:25]
	s_cbranch_vccz .LBB0_1227
	v_readlane_b32 s0, v254, 56
	v_readlane_b32 s1, v254, 57
	s_and_b64 vcc, exec, s[0:1]
	s_cbranch_vccnz .LBB0_1030
	v_readlane_b32 s0, v254, 39
	v_readlane_b32 s1, v254, 40
	s_andn2_b64 vcc, exec, s[0:1]
	s_cbranch_vccnz .LBB0_860
	v_readlane_b32 s0, v253, 10
	v_mbcnt_lo_u32_b32 v0, -1, 0
	v_mbcnt_hi_u32_b32 v0, -1, v0
	s_lshl_b32 s0, s0, 6
	s_waitcnt vmcnt(0)
	s_sub_i32 s0, 0, s0
	v_cmp_eq_u32_e32 vcc, s0, v0
	s_waitcnt vmcnt(0) lgkmcnt(0)
	s_setprio 0
	s_barrier
	s_and_saveexec_b64 s[0:1], vcc
	s_cbranch_execz .LBB0_859
	v_mov_b32_e32 v0, s96
	s_waitcnt vmcnt(0) expcnt(0) lgkmcnt(0)
	ds_read_b32 v2, v0
	ds_read_b32 v0, v0 offset:4
	s_waitcnt lgkmcnt(1)
	v_cmp_ne_u32_e32 vcc, 0, v2
	s_cbranch_vccnz .LBB0_827
	v_readlane_b32 s4, v253, 0
	v_readlane_b32 s5, v253, 1
	s_load_dwordx2 s[2:3], s[4:5], 0x4
	v_readlane_b32 s4, v253, 2
	s_mov_b32 s9, 1
	s_waitcnt lgkmcnt(0)
	s_mul_i32 s8, s2, s4
	s_mul_i32 s8, s8, s3
	s_branch .LBB0_815

; __device__ __forceinline__ unsigned xb_add(unsigned* p, unsigned v) { return __hip_atomic_fetch_add(p, v, __ATOMIC_RELAXED, __HIP_MEMORY_SCOPE_AGENT); }
; #define PH_BEGIN(gp) if (lo <= (gp) && (gp) < hi) { if (!first) xcd_barrier(bar, tid_here(F.wave)); first = false; F.bid = blockIdx.x; asm volatile("" : "+s"(F.ws), "+s"(F.G), "+s"(F.vcu), "+s"(F.bid), "+s"(F.wave)); F.tid = tid_here(F.wave); F.lane = F.tid & 63;
; __device__ __forceinline__ void xcd_barrier(const XcdBarrier& b, int tid) {
;     asm volatile("s_waitcnt vmcnt(0)" ::: "memory");
;     __syncthreads();
;     if (tid == 0) {
;         unsigned* bar = b.bar;
;         __builtin_amdgcn_s_waitcnt(0);
;         unsigned nloc = b.st[0], nx = b.st[1];
;         if (nloc == 0u) { xcd_barrier_complete(bar, b.x, nloc, nx); b.st[0] = nloc; b.st[1] = nx; }
;         const unsigned old = xb_add(&bar[XB_XSUB(b.x)], 1u);
; __global__ void __launch_bounds__(512, 2) fwd_kernel(Args args) {
;     ...
;             PH_BEGIN(gp0 + 2) if (EN & 8) {
.LBB0_1030:
	v_readlane_b32 s0, v254, 54
	s_or_b32 s2, s0, 4
	s_cmp_le_i32 s88, s2
	s_cselect_b64 s[0:1], -1, 0
	s_cmp_lt_i32 s2, s89
	s_cselect_b64 s[2:3], -1, 0
	s_and_b64 s[0:1], s[0:1], s[2:3]
	s_andn2_b64 vcc, exec, s[0:1]
	s_cbranch_vccnz .LBB0_1043
	v_readlane_b32 s0, v253, 8
	v_readlane_b32 s1, v253, 9
	s_xor_b64 s[0:1], s[0:1], -1
	s_andn2_b64 vcc, exec, s[0:1]
	s_cbranch_vccnz .LBB0_1082
	v_readlane_b32 s0, v253, 10
	v_mbcnt_lo_u32_b32 v0, -1, 0
	v_mbcnt_hi_u32_b32 v0, -1, v0
	s_lshl_b32 s0, s0, 6
	s_waitcnt vmcnt(0)
	s_sub_i32 s0, 0, s0
	v_cmp_eq_u32_e32 vcc, s0, v0
	s_waitcnt vmcnt(0) lgkmcnt(0)
	s_setprio 0
	s_barrier
	s_and_saveexec_b64 s[0:1], vcc
	s_cbranch_execz .LBB0_1081
	v_mov_b32_e32 v0, s96
	s_waitcnt vmcnt(0) expcnt(0) lgkmcnt(0)
	ds_read_b32 v2, v0
	ds_read_b32 v0, v0 offset:4
	s_waitcnt lgkmcnt(1)
	v_cmp_ne_u32_e32 vcc, 0, v2
	s_cbranch_vccnz .LBB0_1049
	v_readlane_b32 s4, v253, 0
	v_readlane_b32 s5, v253, 1
	s_load_dwordx2 s[2:3], s[4:5], 0x4
	v_readlane_b32 s4, v253, 2
	s_mov_b32 s9, 1
	s_waitcnt lgkmcnt(0)
	s_mul_i32 s8, s2, s4
	s_mul_i32 s8, s8, s3
	s_branch .LBB0_1036

; __device__ __forceinline__ unsigned xb_add(unsigned* p, unsigned v) { return __hip_atomic_fetch_add(p, v, __ATOMIC_RELAXED, __HIP_MEMORY_SCOPE_AGENT); }
; #define PH_BEGIN(gp) if (lo <= (gp) && (gp) < hi) { if (!first) xcd_barrier(bar, tid_here(F.wave)); first = false; F.bid = blockIdx.x; asm volatile("" : "+s"(F.ws), "+s"(F.G), "+s"(F.vcu), "+s"(F.bid), "+s"(F.wave)); F.tid = tid_here(F.wave); F.lane = F.tid & 63;
; __device__ __forceinline__ void xcd_barrier(const XcdBarrier& b, int tid) {
;     asm volatile("s_waitcnt vmcnt(0)" ::: "memory");
;     __syncthreads();
;     if (tid == 0) {
;         unsigned* bar = b.bar;
;         __builtin_amdgcn_s_waitcnt(0);
;         unsigned nloc = b.st[0], nx = b.st[1];
;         if (nloc == 0u) { xcd_barrier_complete(bar, b.x, nloc, nx); b.st[0] = nloc; b.st[1] = nx; }
;         const unsigned old = xb_add(&bar[XB_XSUB(b.x)], 1u);
; __global__ void __launch_bounds__(512, 2) fwd_kernel(Args args) {
;     ...
;             PH_BEGIN(gp0 + 4) if (EN & 128) {
.LBB0_1227:
	s_nop 0
	v_readlane_b32 s0, v254, 55
	s_cmp_eq_u32 s0, 0
	s_cbranch_scc1 .LBB0_1348
	v_readlane_b32 s0, v254, 54
	s_or_b32 s2, s0, 6
	s_cmp_le_i32 s88, s2
	s_cselect_b64 s[0:1], -1, 0
	s_cmp_lt_i32 s2, s89
	s_cselect_b64 s[2:3], -1, 0
	s_and_b64 s[0:1], s[0:1], s[2:3]
	s_andn2_b64 vcc, exec, s[0:1]
	s_cbranch_vccnz .LBB0_1348
	s_xor_b64 s[0:1], s[42:43], -1
	s_andn2_b64 vcc, exec, s[0:1]
	s_cbranch_vccnz .LBB0_1279
	v_readlane_b32 s0, v254, 59
	v_mbcnt_lo_u32_b32 v0, -1, 0
	v_mbcnt_hi_u32_b32 v0, -1, v0
	s_lshl_b32 s0, s0, 6
	s_waitcnt vmcnt(0)
	s_sub_i32 s0, 0, s0
	v_cmp_eq_u32_e32 vcc, s0, v0
	s_waitcnt vmcnt(0) lgkmcnt(0)
	s_setprio 0
	s_barrier
	s_and_saveexec_b64 s[0:1], vcc
	s_cbranch_execz .LBB0_1278
	v_mov_b32_e32 v0, s96
	s_waitcnt vmcnt(0) expcnt(0) lgkmcnt(0)
	ds_read_b32 v2, v0
	ds_read_b32 v0, v0 offset:4
	s_waitcnt lgkmcnt(1)
	v_cmp_ne_u32_e32 vcc, 0, v2
	s_cbranch_vccnz .LBB0_1246
	v_readlane_b32 s4, v253, 0
	v_readlane_b32 s5, v253, 1
	s_load_dwordx2 s[2:3], s[4:5], 0x4
	v_readlane_b32 s4, v253, 2
	s_mov_b32 s9, 1
	s_waitcnt lgkmcnt(0)
	s_mul_i32 s8, s2, s4
	s_mul_i32 s8, s8, s3
	s_branch .LBB0_1234

; __device__ __forceinline__ unsigned xb_add(unsigned* p, unsigned v) { return __hip_atomic_fetch_add(p, v, __ATOMIC_RELAXED, __HIP_MEMORY_SCOPE_AGENT); }
; #define PH_BEGIN(gp) if (lo <= (gp) && (gp) < hi) { if (!first) xcd_barrier(bar, tid_here(F.wave)); first = false; F.bid = blockIdx.x; asm volatile("" : "+s"(F.ws), "+s"(F.G), "+s"(F.vcu), "+s"(F.bid), "+s"(F.wave)); F.tid = tid_here(F.wave); F.lane = F.tid & 63;
; __device__ __forceinline__ void xcd_barrier(const XcdBarrier& b, int tid) {
;     asm volatile("s_waitcnt vmcnt(0)" ::: "memory");
;     __syncthreads();
;     if (tid == 0) {
;         unsigned* bar = b.bar;
;         __builtin_amdgcn_s_waitcnt(0);
;         unsigned nloc = b.st[0], nx = b.st[1];
;         if (nloc == 0u) { xcd_barrier_complete(bar, b.x, nloc, nx); b.st[0] = nloc; b.st[1] = nx; }
;         const unsigned old = xb_add(&bar[XB_XSUB(b.x)], 1u);
; __global__ void __launch_bounds__(512, 2) fwd_kernel(Args args) {
;     ...
;         PH_BEGIN(gp0 + 6) if (EN & 2048) {
.LBB0_1348:
	v_readlane_b32 s0, v254, 54
	s_add_i32 s2, s0, 8
	s_cmp_le_i32 s88, s2
	s_cselect_b64 s[0:1], -1, 0
	s_cmp_lt_i32 s2, s89
	s_cselect_b64 s[2:3], -1, 0
	s_and_b64 s[0:1], s[0:1], s[2:3]
	s_andn2_b64 vcc, exec, s[0:1]
	s_cbranch_vccnz .LBB0_1483
	s_xor_b64 s[0:1], s[42:43], -1
	s_andn2_b64 vcc, exec, s[0:1]
	s_cbranch_vccnz .LBB0_1399
	v_readlane_b32 s0, v254, 59
	v_mbcnt_lo_u32_b32 v0, -1, 0
	v_mbcnt_hi_u32_b32 v0, -1, v0
	s_lshl_b32 s0, s0, 6
	s_waitcnt vmcnt(0)
	s_sub_i32 s0, 0, s0
	v_cmp_eq_u32_e32 vcc, s0, v0
	s_waitcnt vmcnt(0) lgkmcnt(0)
	s_setprio 0
	s_barrier
	s_and_saveexec_b64 s[0:1], vcc
	s_cbranch_execz .LBB0_1398
	v_mov_b32_e32 v0, s96
	s_waitcnt vmcnt(0) expcnt(0) lgkmcnt(0)
	ds_read_b32 v2, v0
	ds_read_b32 v0, v0 offset:4
	s_waitcnt lgkmcnt(1)
	v_cmp_ne_u32_e32 vcc, 0, v2
	s_cbranch_vccnz .LBB0_1366
	v_readlane_b32 s4, v253, 0
	v_readlane_b32 s5, v253, 1
	s_load_dwordx2 s[2:3], s[4:5], 0x4
	v_readlane_b32 s4, v253, 2
	s_mov_b32 s9, 1
	s_waitcnt lgkmcnt(0)
	s_mul_i32 s8, s2, s4
	s_mul_i32 s8, s8, s3
	s_branch .LBB0_1354

; __device__ __forceinline__ unsigned xb_add(unsigned* p, unsigned v) { return __hip_atomic_fetch_add(p, v, __ATOMIC_RELAXED, __HIP_MEMORY_SCOPE_AGENT); }
; #define PH_BEGIN(gp) if (lo <= (gp) && (gp) < hi) { if (!first) xcd_barrier(bar, tid_here(F.wave)); first = false; F.bid = blockIdx.x; asm volatile("" : "+s"(F.ws), "+s"(F.G), "+s"(F.vcu), "+s"(F.bid), "+s"(F.wave)); F.tid = tid_here(F.wave); F.lane = F.tid & 63;
; __device__ __forceinline__ void xcd_barrier(const XcdBarrier& b, int tid) {
;     asm volatile("s_waitcnt vmcnt(0)" ::: "memory");
;     __syncthreads();
;     if (tid == 0) {
;         unsigned* bar = b.bar;
;         __builtin_amdgcn_s_waitcnt(0);
;         unsigned nloc = b.st[0], nx = b.st[1];
;         if (nloc == 0u) { xcd_barrier_complete(bar, b.x, nloc, nx); b.st[0] = nloc; b.st[1] = nx; }
;         const unsigned old = xb_add(&bar[XB_XSUB(b.x)], 1u);
; __global__ void __launch_bounds__(512, 2) fwd_kernel(Args args) {
;     ...
;             PH_BEGIN(gp0 + 7) if (EN & 4096) {
.LBB0_1483:
	s_xor_b64 s[0:1], s[42:43], -1
	v_writelane_b32 v254, s0, 52
	s_mov_b64 s[2:3], -1
	s_nop 0
	v_writelane_b32 v254, s1, 53
	s_nop 0
	v_readlane_b32 s0, v254, 54
	s_add_i32 s4, s0, 9
	s_cmp_le_i32 s88, s4
	s_cselect_b64 s[0:1], -1, 0
	s_cmp_lt_i32 s4, s89
	s_cselect_b64 s[4:5], -1, 0
	s_and_b64 s[0:1], s[0:1], s[4:5]
	v_cndmask_b32_e64 v0, 0, 1, s[0:1]
	v_readlane_b32 s6, v254, 41
	v_cmp_ne_u32_e64 s[0:1], 1, v0
	v_readlane_b32 s7, v254, 42
	s_andn2_b64 vcc, exec, s[6:7]
	v_writelane_b32 v254, s0, 50
	s_nop 1
	v_writelane_b32 v254, s1, 51
	v_writelane_b32 v253, s0, 4
	s_nop 1
	v_writelane_b32 v253, s1, 5
	s_cbranch_vccnz .LBB0_1651
	v_readlane_b32 s0, v254, 50
	v_readlane_b32 s1, v254, 51
	v_writelane_b32 v253, s42, 8
	s_and_b64 vcc, exec, s[0:1]
	s_mov_b32 s0, s82
	v_writelane_b32 v253, s43, 9
	v_writelane_b32 v253, s0, 4
	s_nop 1
	v_writelane_b32 v253, s1, 5
	v_readlane_b32 s0, v254, 58
	s_nop 1
	v_writelane_b32 v253, s0, 3
	v_readlane_b32 s0, v254, 59
	s_nop 1
	v_writelane_b32 v253, s0, 10
	v_writelane_b32 v253, s46, 6
	s_nop 1
	v_writelane_b32 v253, s47, 7
	s_cbranch_vccnz .LBB0_1650
	v_readlane_b32 s0, v254, 52
	v_readlane_b32 s1, v254, 53
	s_andn2_b64 vcc, exec, s[0:1]
	s_cbranch_vccnz .LBB0_1535
	v_readlane_b32 s0, v254, 59
	v_mbcnt_lo_u32_b32 v0, -1, 0
	v_mbcnt_hi_u32_b32 v0, -1, v0
	s_lshl_b32 s0, s0, 6
	s_waitcnt vmcnt(0)
	s_sub_i32 s0, 0, s0
	v_cmp_eq_u32_e32 vcc, s0, v0
	s_waitcnt vmcnt(0) lgkmcnt(0)
	s_setprio 0
	s_barrier
	s_and_saveexec_b64 s[2:3], vcc
	s_cbranch_execz .LBB0_1534
	v_mov_b32_e32 v0, s96
	s_waitcnt vmcnt(0) expcnt(0) lgkmcnt(0)
	ds_read_b32 v2, v0
	ds_read_b32 v0, v0 offset:4
	s_waitcnt lgkmcnt(1)
	v_cmp_ne_u32_e32 vcc, 0, v2
	s_cbranch_vccnz .LBB0_1502
	v_readlane_b32 s4, v253, 0
	v_readlane_b32 s5, v253, 1
	s_load_dwordx2 s[0:1], s[4:5], 0x4
	v_readlane_b32 s4, v253, 2
	s_waitcnt lgkmcnt(0)
	s_mul_i32 s0, s0, s4
	s_mul_i32 s0, s0, s1
	s_mov_b32 s1, 1
	s_branch .LBB0_1490

; __device__ __forceinline__ unsigned xb_add(unsigned* p, unsigned v) { return __hip_atomic_fetch_add(p, v, __ATOMIC_RELAXED, __HIP_MEMORY_SCOPE_AGENT); }
; #define PH_BEGIN(gp) if (lo <= (gp) && (gp) < hi) { if (!first) xcd_barrier(bar, tid_here(F.wave)); first = false; F.bid = blockIdx.x; asm volatile("" : "+s"(F.ws), "+s"(F.G), "+s"(F.vcu), "+s"(F.bid), "+s"(F.wave)); F.tid = tid_here(F.wave); F.lane = F.tid & 63;
; __device__ __forceinline__ void xcd_barrier(const XcdBarrier& b, int tid) {
;     asm volatile("s_waitcnt vmcnt(0)" ::: "memory");
;     __syncthreads();
;     if (tid == 0) {
;         unsigned* bar = b.bar;
;         __builtin_amdgcn_s_waitcnt(0);
;         unsigned nloc = b.st[0], nx = b.st[1];
;         if (nloc == 0u) { xcd_barrier_complete(bar, b.x, nloc, nx); b.st[0] = nloc; b.st[1] = nx; }
;         const unsigned old = xb_add(&bar[XB_XSUB(b.x)], 1u);
; __global__ void __launch_bounds__(512, 2) fwd_kernel(Args args) {
;     ...
;             PH_BEGIN(gp0 + 7) if (EN & 4096) {
.LBB0_1651:
	s_andn2_b64 vcc, exec, s[2:3]
	s_cbranch_vccnz .LBB0_1805
	v_readlane_b32 s0, v254, 50
	v_readlane_b32 s1, v254, 51
	s_and_b64 vcc, exec, s[0:1]
	s_cbranch_vccnz .LBB0_1804
	v_readlane_b32 s0, v254, 52
	v_readlane_b32 s1, v254, 53
	s_andn2_b64 vcc, exec, s[0:1]
	s_cbranch_vccnz .LBB0_1703
	v_readlane_b32 s0, v254, 59
	v_mbcnt_lo_u32_b32 v0, -1, 0
	v_mbcnt_hi_u32_b32 v0, -1, v0
	s_lshl_b32 s0, s0, 6
	s_waitcnt vmcnt(0)
	s_sub_i32 s0, 0, s0
	v_cmp_eq_u32_e32 vcc, s0, v0
	s_waitcnt vmcnt(0) lgkmcnt(0)
	s_setprio 0
	s_barrier
	s_and_saveexec_b64 s[0:1], vcc
	s_cbranch_execz .LBB0_1702
	v_mov_b32_e32 v0, s96
	s_waitcnt vmcnt(0) expcnt(0) lgkmcnt(0)
	ds_read_b32 v2, v0
	ds_read_b32 v0, v0 offset:4
	s_waitcnt lgkmcnt(1)
	v_cmp_ne_u32_e32 vcc, 0, v2
	s_cbranch_vccnz .LBB0_1670
	v_readlane_b32 s4, v253, 0
	v_readlane_b32 s5, v253, 1
	s_load_dwordx2 s[2:3], s[4:5], 0x4
	v_readlane_b32 s4, v253, 2
	s_mov_b32 s9, 1
	s_waitcnt lgkmcnt(0)
	s_mul_i32 s8, s2, s4
	s_mul_i32 s8, s8, s3
	s_branch .LBB0_1658

; __device__ __forceinline__ unsigned xb_add(unsigned* p, unsigned v) { return __hip_atomic_fetch_add(p, v, __ATOMIC_RELAXED, __HIP_MEMORY_SCOPE_AGENT); }
; #define PH_BEGIN(gp) if (lo <= (gp) && (gp) < hi) { if (!first) xcd_barrier(bar, tid_here(F.wave)); first = false; F.bid = blockIdx.x; asm volatile("" : "+s"(F.ws), "+s"(F.G), "+s"(F.vcu), "+s"(F.bid), "+s"(F.wave)); F.tid = tid_here(F.wave); F.lane = F.tid & 63;
; __device__ __forceinline__ void xcd_barrier(const XcdBarrier& b, int tid) {
;     asm volatile("s_waitcnt vmcnt(0)" ::: "memory");
;     __syncthreads();
;     if (tid == 0) {
;         unsigned* bar = b.bar;
;         __builtin_amdgcn_s_waitcnt(0);
;         unsigned nloc = b.st[0], nx = b.st[1];
;         if (nloc == 0u) { xcd_barrier_complete(bar, b.x, nloc, nx); b.st[0] = nloc; b.st[1] = nx; }
;         const unsigned old = xb_add(&bar[XB_XSUB(b.x)], 1u);
; __global__ void __launch_bounds__(512, 2) fwd_kernel(Args args) {
;     ...
;     if (F.G != 256) { PH_BEGIN(34) if (EN & 8192) phase_final(F); PH_END }
.LBB0_1807:
	v_readlane_b32 s0, v253, 4
	v_readlane_b32 s20, v254, 35
	s_cmpk_lg_i32 s0, 0x100
	v_readlane_b32 s21, v254, 36
	v_readlane_b32 s1, v253, 5
	v_readlane_b32 s22, v254, 37
	v_readlane_b32 s23, v254, 38
	s_cbranch_scc0 .LBB0_1862
	s_cmp_lt_i32 s88, 35
	s_cselect_b64 s[0:1], -1, 0
	s_cmp_gt_i32 s89, 34
	s_cselect_b64 s[2:3], -1, 0
	s_and_b64 s[0:1], s[0:1], s[2:3]
	s_andn2_b64 vcc, exec, s[0:1]
	s_cbranch_vccnz .LBB0_1862
	v_readlane_b32 s0, v253, 8
	v_readlane_b32 s1, v253, 9
	s_xor_b64 s[0:1], s[0:1], -1
	s_andn2_b64 vcc, exec, s[0:1]
	s_cbranch_vccnz .LBB0_1859
	v_readlane_b32 s0, v253, 10
	v_mbcnt_lo_u32_b32 v0, -1, 0
	v_mbcnt_hi_u32_b32 v0, -1, v0
	s_lshl_b32 s0, s0, 6
	s_waitcnt vmcnt(0)
	s_sub_i32 s0, 0, s0
	v_cmp_eq_u32_e32 vcc, s0, v0
	s_waitcnt vmcnt(0) lgkmcnt(0)
	s_setprio 0
	s_barrier
	s_and_saveexec_b64 s[0:1], vcc
	v_readlane_b32 s18, v254, 13
	v_readlane_b32 s19, v254, 14
	s_cbranch_execz .LBB0_1858
	v_mov_b32_e32 v0, s96
	s_waitcnt vmcnt(0) expcnt(0) lgkmcnt(0)
	ds_read_b32 v2, v0
	ds_read_b32 v0, v0 offset:4
	s_waitcnt lgkmcnt(1)
	v_cmp_ne_u32_e32 vcc, 0, v2
	s_cbranch_vccnz .LBB0_1826
	v_readlane_b32 s4, v253, 0
	v_readlane_b32 s5, v253, 1
	s_load_dwordx2 s[2:3], s[4:5], 0x4
	v_readlane_b32 s4, v253, 2
	s_mov_b32 s8, 1
	v_mov_b32_e32 v16, 0
	s_waitcnt lgkmcnt(0)
	s_mul_i32 s9, s2, s4
	s_mul_i32 s9, s9, s3
	s_branch .LBB0_1814
